# v019 + C2b epilogue batched gate loads + redundant canonicalising v_max dropped in A1 score loops
# speedup vs baseline: 1.0071x; 1.0046x over previous
; #define MFMA32(a, b, c) __builtin_amdgcn_mfma_f32_32x32x16_bf16((a), (b), (c), 0, 0, 0)
; DI void phaseA1(const Params& p, int vblock, int nvblocks, int ubegin, int uend, char* smem) {
;     ...
;     for (int kb = wid; kb < nt; kb += 16) {
;       bf16x8 kf[4][4];
; #pragma unroll
;       for (int j = 0; j < 4; ++j) {
;         const int kt = kb + 4 * j < nt ? kb + 4 * j : kb;
;         const bf16_t* q_ = kib + (size_t)kt * 2048;
;         kf[j][0] = ld16(q_); kf[j][1] = ld16(q_ + 512); kf[j][2] = ld16(q_ + 1024); kf[j][3] = ld16(q_ + 1536);
;       }
; #pragma unroll
;       for (int j = 0; j < 4; ++j) {
;         const int kt = kb + 4 * j;
;         if (kt < nt) {
;           f32x16 s0, s1;
; #pragma unroll
;           for (int e = 0; e < 16; ++e) { s0[e] = 0.f; s1[e] = 0.f; }
; #pragma unroll
;           for (int ks = 0; ks < 4; ++ks) { s0 = MFMA32(af0[ks], kf[j][ks], s0); s1 = MFMA32(af1[ks], kf[j][ks], s1); }
;           float a0 = 0.f, a1 = 0.f, a2 = 0.f, a3 = 0.f;
; #pragma unroll
;           for (int e = 0; e < 8; ++e) {
;             a0 += wr0[e] * fmaxf(s0[e], 0.f); a1 += wr0[8 + e] * fmaxf(s0[8 + e], 0.f);
;             a2 += wr1[e] * fmaxf(s1[e], 0.f); a3 += wr1[8 + e] * fmaxf(s1[8 + e], 0.f);
;           }
;           const int key = kt * 32 + r;
;           sc[(hh * 2 + 0) * 2048 + key] = a0 + 0.0f;
;           sc[(hh * 2 + 1) * 2048 + key] = a1 + 0.0f;
;           sc[(4 + hh * 2 + 0) * 2048 + key] = a2 + 0.0f;
;           sc[(4 + hh * 2 + 1) * 2048 + key] = a3 + 0.0f;
.LBB0_346:
	v_add_u32_e32 v152, 4, v151
	v_cmp_lt_i32_e64 s[72:73], s89, v152
	v_cmp_ge_i32_e64 s[74:75], s89, v152
	s_nop 0
	v_cndmask_b32_e64 v172, v152, v151, s[72:73]
	v_ashrrev_i32_e32 v173, 31, v172
	v_lshlrev_b64 v[172:173], 12, v[172:173]
	v_lshl_add_u64 v[172:173], v[114:115], 0, v[172:173]
	global_load_dwordx4 v[190:193], v[172:173], off
	global_load_dwordx4 v[194:197], v[172:173], off offset:1024
	global_load_dwordx4 v[198:201], v[172:173], off offset:2048
	global_load_dwordx4 v[202:205], v[172:173], off offset:3072
	s_waitcnt vmcnt(7)
	v_mfma_f32_32x32x16_bf16 v[18:33], v[34:37], v[216:219], 0
	v_mfma_f32_32x32x16_bf16 v[2:17], v[58:61], v[216:219], 0
	s_waitcnt vmcnt(6)
	v_mfma_f32_32x32x16_bf16 v[18:33], v[38:41], v[220:223], v[18:33]
	v_mfma_f32_32x32x16_bf16 v[2:17], v[42:45], v[220:223], v[2:17]
	v_add_u32_e32 v66, 8, v151
	v_add_u32_e32 v67, 12, v151
	v_cmp_lt_i32_e32 vcc, s89, v66
	v_cmp_lt_i32_e64 s[2:3], s89, v67
	v_cmp_ge_i32_e64 s[70:71], s89, v66
	v_cndmask_b32_e32 v66, v66, v151, vcc
	v_cndmask_b32_e64 v68, v67, v151, s[2:3]
	v_cmp_ge_i32_e32 vcc, s89, v67
	v_ashrrev_i32_e32 v67, 31, v66
	v_ashrrev_i32_e32 v69, 31, v68
	v_lshlrev_b64 v[66:67], 12, v[66:67]
	v_lshlrev_b64 v[68:69], 12, v[68:69]
	v_lshl_add_u64 v[66:67], v[114:115], 0, v[66:67]
	v_lshl_add_u64 v[68:69], v[114:115], 0, v[68:69]
	s_waitcnt vmcnt(5)
	v_mfma_f32_32x32x16_bf16 v[18:33], v[50:53], v[224:227], v[18:33]
	v_mfma_f32_32x32x16_bf16 v[2:17], v[46:49], v[224:227], v[2:17]
	global_load_dwordx4 v[94:97], v[66:67], off
	global_load_dwordx4 v[90:93], v[66:67], off offset:1024
	global_load_dwordx4 v[86:89], v[66:67], off offset:2048
	global_load_dwordx4 v[82:85], v[66:67], off offset:3072
	global_load_dwordx4 v[78:81], v[68:69], off
	global_load_dwordx4 v[74:77], v[68:69], off offset:1024
	global_load_dwordx4 v[70:73], v[68:69], off offset:2048
	s_nop 0
	global_load_dwordx4 v[66:69], v[68:69], off offset:3072
	s_waitcnt vmcnt(12)
	v_mfma_f32_32x32x16_bf16 v[18:33], v[54:57], v[240:243], v[18:33]
	v_mfma_f32_32x32x16_bf16 v[2:17], v[62:65], v[240:243], v[2:17]
	v_add_u32_e32 v174, 16, v151
	v_min_i32_e32 v174, s89, v174
	v_ashrrev_i32_e32 v175, 31, v174
	v_lshlrev_b64 v[174:175], 12, v[174:175]
	v_lshl_add_u64 v[174:175], v[114:115], 0, v[174:175]
	global_load_dwordx4 v[216:219], v[174:175], off
	global_load_dwordx4 v[220:223], v[174:175], off offset:1024
	global_load_dwordx4 v[224:227], v[174:175], off offset:2048
	global_load_dwordx4 v[240:243], v[174:175], off offset:3072
	s_nop 10
	v_max_f32_e32 v18, 0, v18
	v_max_f32_e32 v19, 0, v19
	v_fma_f32 v18, v111, v18, 0
	v_max_f32_e32 v26, 0, v26
	v_max_f32_e32 v20, 0, v20
	v_fmac_f32_e32 v18, v119, v19
	v_max_f32_e32 v27, 0, v27
	v_max_f32_e32 v21, 0, v21
	v_fma_f32 v26, v126, v26, 0
	v_fmac_f32_e32 v18, v120, v20
	v_max_f32_e32 v2, 0, v2
	v_max_f32_e32 v28, 0, v28
	v_max_f32_e32 v22, 0, v22
	v_fmac_f32_e32 v26, v127, v27
	v_fmac_f32_e32 v18, v121, v21
	v_max_f32_e32 v3, 0, v3
	v_max_f32_e32 v29, 0, v29
	v_max_f32_e32 v23, 0, v23
	v_fma_f32 v2, v134, v2, 0
	v_fmac_f32_e32 v26, v128, v28
	v_fmac_f32_e32 v18, v122, v22
	v_max_f32_e32 v10, 0, v10
	v_max_f32_e32 v4, 0, v4
	v_max_f32_e32 v30, 0, v30
	v_max_f32_e32 v24, 0, v24
	v_fmac_f32_e32 v2, v135, v3
	v_fmac_f32_e32 v26, v129, v29
	v_fmac_f32_e32 v18, v123, v23
	v_max_f32_e32 v3, v25, v25
	v_max_f32_e32 v11, 0, v11
	v_max_f32_e32 v5, 0, v5
	v_max_f32_e32 v31, 0, v31
	v_fma_f32 v10, v142, v10, 0
	v_fmac_f32_e32 v2, v136, v4
	v_fmac_f32_e32 v26, v130, v30
	v_fmac_f32_e32 v18, v124, v24
	v_max_f32_e32 v3, 0, v3
	v_max_f32_e32 v12, 0, v12
	v_max_f32_e32 v6, 0, v6
	v_max_f32_e32 v32, 0, v32
	v_fmac_f32_e32 v10, v143, v11
	v_fmac_f32_e32 v2, v137, v5
	v_fmac_f32_e32 v26, v131, v31
	v_fmac_f32_e32 v18, v125, v3
	v_max_f32_e32 v3, v33, v33
	v_max_f32_e32 v13, 0, v13
	v_max_f32_e32 v7, 0, v7
	v_fmac_f32_e32 v10, v144, v12
	v_fmac_f32_e32 v2, v138, v6
	v_fmac_f32_e32 v26, v132, v32
	v_max_f32_e32 v3, 0, v3
	v_max_f32_e32 v14, 0, v14
	v_max_f32_e32 v8, 0, v8
	v_fmac_f32_e32 v10, v145, v13
	v_fmac_f32_e32 v2, v139, v7
	v_fmac_f32_e32 v26, v133, v3
	v_max_f32_e32 v3, v9, v9
	v_max_f32_e32 v15, 0, v15
	v_fmac_f32_e32 v10, v146, v14
	v_fmac_f32_e32 v2, v140, v8
	v_max_f32_e32 v3, 0, v3
	v_max_f32_e32 v16, 0, v16
	v_fmac_f32_e32 v10, v147, v15
	v_fmac_f32_e32 v2, v141, v3
	v_max_f32_e32 v3, v17, v17
	v_fmac_f32_e32 v10, v148, v16
	v_max_f32_e32 v3, 0, v3
	v_fmac_f32_e32 v10, v149, v3
	v_add_f32_e32 v3, 0, v18
	v_add_f32_e32 v4, 0, v26
	ds_write2st64_b32 v150, v3, v4 offset1:32
	v_add_f32_e32 v2, 0, v2
	v_add_f32_e32 v3, 0, v10
	ds_write2st64_b32 v150, v2, v3 offset0:128 offset1:160
	s_and_saveexec_b64 s[2:3], s[74:75]
	s_cbranch_execz .LBB0_349
; #define MFMA32(a, b, c) __builtin_amdgcn_mfma_f32_32x32x16_bf16((a), (b), (c), 0, 0, 0)
; DI void phaseA1(const Params& p, int vblock, int nvblocks, int ubegin, int uend, char* smem) {
;     ...
; #pragma unroll
;       for (int j = 0; j < 4; ++j) {
;         const int kt = kb + 4 * j;
;         if (kt < nt) {
;           f32x16 s0, s1;
; #pragma unroll
;           for (int e = 0; e < 16; ++e) { s0[e] = 0.f; s1[e] = 0.f; }
; #pragma unroll
;           for (int ks = 0; ks < 4; ++ks) { s0 = MFMA32(af0[ks], kf[j][ks], s0); s1 = MFMA32(af1[ks], kf[j][ks], s1); }
;           float a0 = 0.f, a1 = 0.f, a2 = 0.f, a3 = 0.f;
; #pragma unroll
;           for (int e = 0; e < 8; ++e) {
;             a0 += wr0[e] * fmaxf(s0[e], 0.f); a1 += wr0[8 + e] * fmaxf(s0[8 + e], 0.f);
;             a2 += wr1[e] * fmaxf(s1[e], 0.f); a3 += wr1[8 + e] * fmaxf(s1[8 + e], 0.f);
;           }
;           const int key = kt * 32 + r;
;           sc[(hh * 2 + 0) * 2048 + key] = a0 + 0.0f;
;           sc[(hh * 2 + 1) * 2048 + key] = a1 + 0.0f;
;           sc[(4 + hh * 2 + 0) * 2048 + key] = a2 + 0.0f;
;           sc[(4 + hh * 2 + 1) * 2048 + key] = a3 + 0.0f;
	s_waitcnt vmcnt(12)
	v_mfma_f32_32x32x16_bf16 v[18:33], v[34:37], v[190:193], 0
	v_mfma_f32_32x32x16_bf16 v[2:17], v[58:61], v[190:193], 0
	v_mfma_f32_32x32x16_bf16 v[18:33], v[38:41], v[194:197], v[18:33]
	v_mfma_f32_32x32x16_bf16 v[2:17], v[42:45], v[194:197], v[2:17]
	v_mfma_f32_32x32x16_bf16 v[18:33], v[50:53], v[198:201], v[18:33]
	v_mfma_f32_32x32x16_bf16 v[2:17], v[46:49], v[198:201], v[2:17]
	v_mfma_f32_32x32x16_bf16 v[18:33], v[54:57], v[202:205], v[18:33]
	s_nop 11
	v_mfma_f32_32x32x16_bf16 v[2:17], v[62:65], v[202:205], v[2:17]
	v_max_f32_e32 v18, 0, v18
	v_max_f32_e32 v26, 0, v26
	s_nop 4
	s_nop 4
	v_max_f32_e32 v2, 0, v2
	v_max_f32_e32 v10, 0, v10
	v_max_f32_e32 v19, 0, v19
	v_max_f32_e32 v27, 0, v27
	v_fma_f32 v18, v111, v18, 0
	v_fma_f32 v26, v126, v26, 0
	v_max_f32_e32 v3, 0, v3
	v_max_f32_e32 v11, 0, v11
	v_max_f32_e32 v20, 0, v20
	v_max_f32_e32 v28, 0, v28
	v_fma_f32 v2, v134, v2, 0
	v_fma_f32 v10, v142, v10, 0
	v_fmac_f32_e32 v18, v119, v19
	v_fmac_f32_e32 v26, v127, v27
	v_max_f32_e32 v4, 0, v4
	v_max_f32_e32 v12, 0, v12
	v_max_f32_e32 v21, 0, v21
	v_max_f32_e32 v29, 0, v29
	v_fmac_f32_e32 v2, v135, v3
	v_fmac_f32_e32 v10, v143, v11
	v_fmac_f32_e32 v18, v120, v20
	v_fmac_f32_e32 v26, v128, v28
	v_max_f32_e32 v5, 0, v5
	v_max_f32_e32 v13, 0, v13
	v_max_f32_e32 v22, 0, v22
	v_max_f32_e32 v30, 0, v30
	v_fmac_f32_e32 v2, v136, v4
	v_fmac_f32_e32 v10, v144, v12
	v_fmac_f32_e32 v18, v121, v21
	v_fmac_f32_e32 v26, v129, v29
	v_max_f32_e32 v6, 0, v6
	v_max_f32_e32 v14, 0, v14
	v_max_f32_e32 v23, 0, v23
	v_max_f32_e32 v31, 0, v31
	v_fmac_f32_e32 v2, v137, v5
	v_fmac_f32_e32 v10, v145, v13
	v_fmac_f32_e32 v18, v122, v22
	v_fmac_f32_e32 v26, v130, v30
	v_max_f32_e32 v7, 0, v7
	v_max_f32_e32 v15, 0, v15
	v_max_f32_e32 v24, 0, v24
	v_max_f32_e32 v32, 0, v32
	v_fmac_f32_e32 v2, v138, v6
	v_fmac_f32_e32 v10, v146, v14
	v_fmac_f32_e32 v18, v123, v23
	v_fmac_f32_e32 v26, v131, v31
	v_max_f32_e32 v8, 0, v8
	v_max_f32_e32 v16, 0, v16
	v_max_f32_e32 v25, 0, v25
	v_max_f32_e32 v33, 0, v33
	v_fmac_f32_e32 v2, v139, v7
	v_fmac_f32_e32 v10, v147, v15
	v_fmac_f32_e32 v18, v124, v24
	v_fmac_f32_e32 v26, v132, v32
	v_max_f32_e32 v9, 0, v9
	v_max_f32_e32 v17, 0, v17
	v_fmac_f32_e32 v2, v140, v8
	v_fmac_f32_e32 v10, v148, v16
	v_fmac_f32_e32 v18, v125, v25
	v_fmac_f32_e32 v26, v133, v33
	v_fmac_f32_e32 v2, v141, v9
	v_fmac_f32_e32 v10, v149, v17
	v_add_f32_e32 v3, 0, v18
	v_add_f32_e32 v4, 0, v26
	v_add_f32_e32 v2, 0, v2
	v_add_f32_e32 v5, 0, v10
	ds_write2st64_b32 v150, v3, v4 offset0:2 offset1:34
	ds_write2st64_b32 v150, v2, v5 offset0:130 offset1:162
	s_or_b64 exec, exec, s[2:3]
	s_and_saveexec_b64 s[2:3], s[70:71]
	s_cbranch_execnz .LBB0_350

; #define MFMA32(a, b, c) __builtin_amdgcn_mfma_f32_32x32x16_bf16((a), (b), (c), 0, 0, 0)
; DI void phaseA1(const Params& p, int vblock, int nvblocks, int ubegin, int uend, char* smem) {
;     ...
; #pragma unroll
;       for (int j = 0; j < 4; ++j) {
;         const int kt = kb + 4 * j;
;         if (kt < nt) {
;           f32x16 s0, s1;
; #pragma unroll
;           for (int e = 0; e < 16; ++e) { s0[e] = 0.f; s1[e] = 0.f; }
; #pragma unroll
;           for (int ks = 0; ks < 4; ++ks) { s0 = MFMA32(af0[ks], kf[j][ks], s0); s1 = MFMA32(af1[ks], kf[j][ks], s1); }
;           float a0 = 0.f, a1 = 0.f, a2 = 0.f, a3 = 0.f;
; #pragma unroll
;           for (int e = 0; e < 8; ++e) {
;             a0 += wr0[e] * fmaxf(s0[e], 0.f); a1 += wr0[8 + e] * fmaxf(s0[8 + e], 0.f);
;             a2 += wr1[e] * fmaxf(s1[e], 0.f); a3 += wr1[8 + e] * fmaxf(s1[8 + e], 0.f);
;           }
;           const int key = kt * 32 + r;
;           sc[(hh * 2 + 0) * 2048 + key] = a0 + 0.0f;
;           sc[(hh * 2 + 1) * 2048 + key] = a1 + 0.0f;
;           sc[(4 + hh * 2 + 0) * 2048 + key] = a2 + 0.0f;
;           sc[(4 + hh * 2 + 1) * 2048 + key] = a3 + 0.0f;
.LBB0_350:
	s_waitcnt vmcnt(11)
	v_mfma_f32_32x32x16_bf16 v[2:17], v[58:61], v[94:97], 0
	v_mfma_f32_32x32x16_bf16 v[18:33], v[34:37], v[94:97], 0
	s_waitcnt vmcnt(10)
	v_mfma_f32_32x32x16_bf16 v[2:17], v[42:45], v[90:93], v[2:17]
	v_mfma_f32_32x32x16_bf16 v[18:33], v[38:41], v[90:93], v[18:33]
	s_waitcnt vmcnt(9)
	v_mfma_f32_32x32x16_bf16 v[2:17], v[46:49], v[86:89], v[2:17]
	v_mfma_f32_32x32x16_bf16 v[18:33], v[50:53], v[86:89], v[18:33]
	s_waitcnt vmcnt(8)
	v_mfma_f32_32x32x16_bf16 v[2:17], v[62:65], v[82:85], v[2:17]
	v_mfma_f32_32x32x16_bf16 v[18:33], v[54:57], v[82:85], v[18:33]
	s_nop 10
	v_max_f32_e32 v2, 0, v2
	v_fma_f32 v2, v134, v2, 0
	v_max_f32_e32 v3, 0, v3
	v_max_f32_e32 v10, 0, v10
	v_fmac_f32_e32 v2, v135, v3
	v_max_f32_e32 v3, v11, v11
	v_max_f32_e32 v18, 0, v18
	v_fma_f32 v10, v142, v10, 0
	v_max_f32_e32 v3, 0, v3
	v_fma_f32 v18, v111, v18, 0
	v_max_f32_e32 v19, 0, v19
	v_fmac_f32_e32 v10, v143, v3
	v_max_f32_e32 v3, v20, v20
	v_max_f32_e32 v26, 0, v26
	v_fmac_f32_e32 v18, v119, v19
	v_max_f32_e32 v19, v27, v27
	v_max_f32_e32 v3, 0, v3
	v_fma_f32 v26, v126, v26, 0
	v_max_f32_e32 v19, 0, v19
	v_fmac_f32_e32 v18, v120, v3
	v_max_f32_e32 v3, v28, v28
	v_fmac_f32_e32 v26, v127, v19
	v_max_f32_e32 v3, 0, v3
	v_fmac_f32_e32 v26, v128, v3
	v_max_f32_e32 v3, v4, v4
	v_max_f32_e32 v3, 0, v3
	v_fmac_f32_e32 v2, v136, v3
	v_max_f32_e32 v3, v12, v12
	v_max_f32_e32 v3, 0, v3
	v_fmac_f32_e32 v10, v144, v3
	v_max_f32_e32 v3, v21, v21
	v_max_f32_e32 v3, 0, v3
	v_fmac_f32_e32 v18, v121, v3
	v_max_f32_e32 v3, v29, v29
	v_max_f32_e32 v3, 0, v3
	v_fmac_f32_e32 v26, v129, v3
	v_max_f32_e32 v3, v5, v5
	v_max_f32_e32 v3, 0, v3
	v_fmac_f32_e32 v2, v137, v3
	v_max_f32_e32 v3, v13, v13
	v_max_f32_e32 v3, 0, v3
	v_fmac_f32_e32 v10, v145, v3
	v_max_f32_e32 v3, v22, v22
	v_max_f32_e32 v3, 0, v3
	v_fmac_f32_e32 v18, v122, v3
	v_max_f32_e32 v3, v30, v30
	v_max_f32_e32 v3, 0, v3
	v_fmac_f32_e32 v26, v130, v3
	v_max_f32_e32 v3, v6, v6
	v_max_f32_e32 v3, 0, v3
	v_fmac_f32_e32 v2, v138, v3
	v_max_f32_e32 v3, v14, v14
	v_max_f32_e32 v3, 0, v3
	v_fmac_f32_e32 v10, v146, v3
	v_max_f32_e32 v3, v23, v23
	v_max_f32_e32 v3, 0, v3
	v_fmac_f32_e32 v18, v123, v3
	v_max_f32_e32 v3, v31, v31
	v_max_f32_e32 v3, 0, v3
	v_fmac_f32_e32 v26, v131, v3
	v_max_f32_e32 v3, v7, v7
	v_max_f32_e32 v3, 0, v3
	v_fmac_f32_e32 v2, v139, v3
	v_max_f32_e32 v3, v15, v15
	v_max_f32_e32 v3, 0, v3
	v_fmac_f32_e32 v10, v147, v3
	v_max_f32_e32 v3, v24, v24
	v_max_f32_e32 v3, 0, v3
	v_fmac_f32_e32 v18, v124, v3
	v_max_f32_e32 v3, v32, v32
	v_max_f32_e32 v3, 0, v3
	v_fmac_f32_e32 v26, v132, v3
	v_max_f32_e32 v3, v8, v8
	v_max_f32_e32 v3, 0, v3
	v_fmac_f32_e32 v2, v140, v3
	v_max_f32_e32 v3, v16, v16
	v_max_f32_e32 v3, 0, v3
	v_fmac_f32_e32 v10, v148, v3
	v_max_f32_e32 v3, v25, v25
	v_max_f32_e32 v3, 0, v3
	v_fmac_f32_e32 v18, v125, v3
	v_max_f32_e32 v3, v33, v33
	v_max_f32_e32 v3, 0, v3
	v_fmac_f32_e32 v26, v133, v3
	v_max_f32_e32 v3, v9, v9
	v_max_f32_e32 v3, 0, v3
	v_fmac_f32_e32 v2, v141, v3
	v_max_f32_e32 v3, v17, v17
	v_max_f32_e32 v3, 0, v3
	v_fmac_f32_e32 v10, v149, v3
	v_add_f32_e32 v3, 0, v18
	v_add_f32_e32 v4, 0, v26
	ds_write2st64_b32 v150, v3, v4 offset0:4 offset1:36
	v_add_f32_e32 v2, 0, v2
	v_add_f32_e32 v3, 0, v10
	ds_write2st64_b32 v150, v2, v3 offset0:132 offset1:164
	s_or_b64 exec, exec, s[2:3]
	s_and_saveexec_b64 s[2:3], vcc
	s_cbranch_execz .LBB0_345
.LBB0_351:
	s_waitcnt vmcnt(7)
	v_mfma_f32_32x32x16_bf16 v[2:17], v[58:61], v[78:81], 0
	v_mfma_f32_32x32x16_bf16 v[18:33], v[34:37], v[78:81], 0
	s_waitcnt vmcnt(6)
	v_mfma_f32_32x32x16_bf16 v[2:17], v[42:45], v[74:77], v[2:17]
	v_mfma_f32_32x32x16_bf16 v[18:33], v[38:41], v[74:77], v[18:33]
	s_waitcnt vmcnt(5)
	v_mfma_f32_32x32x16_bf16 v[2:17], v[46:49], v[70:73], v[2:17]
	v_mfma_f32_32x32x16_bf16 v[18:33], v[50:53], v[70:73], v[18:33]
	s_waitcnt vmcnt(4)
	v_mfma_f32_32x32x16_bf16 v[2:17], v[62:65], v[66:69], v[2:17]
	v_mfma_f32_32x32x16_bf16 v[18:33], v[54:57], v[66:69], v[18:33]
	s_nop 10
	v_max_f32_e32 v2, 0, v2
	v_fma_f32 v2, v134, v2, 0
	v_max_f32_e32 v3, 0, v3
	v_max_f32_e32 v10, 0, v10
	v_fmac_f32_e32 v2, v135, v3
	v_max_f32_e32 v3, v11, v11
	v_max_f32_e32 v18, 0, v18
	v_fma_f32 v10, v142, v10, 0
	v_max_f32_e32 v3, 0, v3
	v_fma_f32 v18, v111, v18, 0
	v_max_f32_e32 v19, 0, v19
	v_fmac_f32_e32 v10, v143, v3
	v_max_f32_e32 v3, v20, v20
	v_max_f32_e32 v26, 0, v26
	v_fmac_f32_e32 v18, v119, v19
	v_max_f32_e32 v19, v27, v27
	v_max_f32_e32 v3, 0, v3
	v_fma_f32 v26, v126, v26, 0
	v_max_f32_e32 v19, 0, v19
	v_fmac_f32_e32 v18, v120, v3
	v_max_f32_e32 v3, v28, v28
	v_fmac_f32_e32 v26, v127, v19
	v_max_f32_e32 v3, 0, v3
	v_fmac_f32_e32 v26, v128, v3
	v_max_f32_e32 v3, v4, v4
	v_max_f32_e32 v3, 0, v3
	v_fmac_f32_e32 v2, v136, v3
	v_max_f32_e32 v3, v12, v12
	v_max_f32_e32 v3, 0, v3
	v_fmac_f32_e32 v10, v144, v3
	v_max_f32_e32 v3, v21, v21
	v_max_f32_e32 v3, 0, v3
	v_fmac_f32_e32 v18, v121, v3
	v_max_f32_e32 v3, v29, v29
	v_max_f32_e32 v3, 0, v3
	v_fmac_f32_e32 v26, v129, v3
	v_max_f32_e32 v3, v5, v5
	v_max_f32_e32 v3, 0, v3
	v_fmac_f32_e32 v2, v137, v3
	v_max_f32_e32 v3, v13, v13
	v_max_f32_e32 v3, 0, v3
	v_fmac_f32_e32 v10, v145, v3
	v_max_f32_e32 v3, v22, v22
	v_max_f32_e32 v3, 0, v3
	v_fmac_f32_e32 v18, v122, v3
	v_max_f32_e32 v3, v30, v30
	v_max_f32_e32 v3, 0, v3
	v_fmac_f32_e32 v26, v130, v3
	v_max_f32_e32 v3, v6, v6
	v_max_f32_e32 v3, 0, v3
	v_fmac_f32_e32 v2, v138, v3
	v_max_f32_e32 v3, v14, v14
	v_max_f32_e32 v3, 0, v3
	v_fmac_f32_e32 v10, v146, v3
	v_max_f32_e32 v3, v23, v23
	v_max_f32_e32 v3, 0, v3
	v_fmac_f32_e32 v18, v123, v3
	v_max_f32_e32 v3, v31, v31
	v_max_f32_e32 v3, 0, v3
	v_fmac_f32_e32 v26, v131, v3
	v_max_f32_e32 v3, v7, v7
	v_max_f32_e32 v3, 0, v3
	v_fmac_f32_e32 v2, v139, v3
	v_max_f32_e32 v3, v15, v15
	v_max_f32_e32 v3, 0, v3
	v_fmac_f32_e32 v10, v147, v3
	v_max_f32_e32 v3, v24, v24
	v_max_f32_e32 v3, 0, v3
	v_fmac_f32_e32 v18, v124, v3
	v_max_f32_e32 v3, v32, v32
	v_max_f32_e32 v3, 0, v3
	v_fmac_f32_e32 v26, v132, v3
	v_max_f32_e32 v3, v8, v8
	v_max_f32_e32 v3, 0, v3
	v_fmac_f32_e32 v2, v140, v3
	v_max_f32_e32 v3, v16, v16
	v_max_f32_e32 v3, 0, v3
	v_fmac_f32_e32 v10, v148, v3
	v_max_f32_e32 v3, v25, v25
	v_max_f32_e32 v3, 0, v3
	v_fmac_f32_e32 v18, v125, v3
	v_max_f32_e32 v3, v33, v33
	v_max_f32_e32 v3, 0, v3
	v_fmac_f32_e32 v26, v133, v3
	v_max_f32_e32 v3, v9, v9
	v_max_f32_e32 v3, 0, v3
	v_fmac_f32_e32 v2, v141, v3
	v_max_f32_e32 v3, v17, v17
	v_max_f32_e32 v3, 0, v3
	v_fmac_f32_e32 v10, v149, v3
	v_add_f32_e32 v3, 0, v18
	v_add_f32_e32 v4, 0, v26
	ds_write2st64_b32 v150, v3, v4 offset0:6 offset1:38
	v_add_f32_e32 v2, 0, v2
	v_add_f32_e32 v3, 0, v10
	ds_write2st64_b32 v150, v2, v3 offset0:134 offset1:166
	s_branch .LBB0_345
